# row-scale loads of the SwiGLU/scale epilogues issued from the K-loop's last iteration (after its final barrier), single accumulator zeroing
# baseline (speedup 1.0000x reference)
.LBB0_625:
	s_add_i32 s35, s34, 2
	s_add_u32 s56, s6, 0x80
	s_addc_u32 s57, s7, 0
	s_add_i32 s95, 0, 0x10000
	s_cmp_eq_u32 s27, s34
	s_cselect_b32 s57, s39, s57
	s_cselect_b32 s56, s38, s56
	s_cselect_b32 s75, s13, s2
	s_cselect_b32 s74, s12, s1
	s_add_i32 s34, 0, 0x14000
	v_add_u32_e32 v140, s95, v217
	v_add_u32_e32 v156, s34, v217
	s_waitcnt lgkmcnt(0)
	ds_read_b128 v[128:131], v140
	ds_read_b128 v[132:135], v140 offset:1024
	ds_read_b128 v[136:139], v140 offset:2048
	ds_read_b128 v[140:143], v140 offset:3072
	ds_read_b128 v[144:147], v156
	ds_read_b128 v[148:151], v156 offset:1024
	ds_read_b128 v[152:155], v156 offset:2048
	ds_read_b128 v[170:173], v156 offset:3072
	v_lshl_add_u64 v[234:235], s[6:7], 0, v[166:167]
	s_add_i32 m0, s44, 0xc000
	ds_read_b128 v[174:177], v220
	ds_read_b128 v[178:181], v220 offset:1024
	ds_read_b128 v[182:185], v220 offset:2048
	ds_read_b128 v[186:189], v220 offset:3072
	ds_read_b128 v[190:193], v220 offset:4096
	ds_read_b128 v[222:225], v220 offset:5120
	ds_read_b128 v[226:229], v220 offset:6144
	ds_read_b128 v[230:233], v220 offset:7168
	global_load_lds_dwordx4 v[234:235], off
	v_lshl_add_u64 v[234:235], s[6:7], 0, v[168:169]
	s_add_i32 m0, s44, 0xe000
	s_nop 0
	global_load_lds_dwordx4 v[234:235], off
	s_waitcnt vmcnt(8)
	s_waitcnt lgkmcnt(0)
	s_barrier
	s_setprio 1
	s_waitcnt lgkmcnt(0)
	v_mfma_f32_16x16x32_bf16 v[120:123], v[128:131], v[174:177], v[120:123]
	v_mfma_f32_16x16x32_bf16 v[112:115], v[136:139], v[174:177], v[112:115]
	v_mfma_f32_16x16x32_bf16 v[104:107], v[128:131], v[182:185], v[104:107]
	v_mfma_f32_16x16x32_bf16 v[96:99], v[136:139], v[182:185], v[96:99]
	v_mfma_f32_16x16x32_bf16 v[88:91], v[128:131], v[190:193], v[88:91]
	v_mfma_f32_16x16x32_bf16 v[80:83], v[136:139], v[190:193], v[80:83]
	v_mfma_f32_16x16x32_bf16 v[72:75], v[128:131], v[226:229], v[72:75]
	v_mfma_f32_16x16x32_bf16 v[64:67], v[136:139], v[226:229], v[64:67]
	v_mfma_f32_16x16x32_bf16 v[120:123], v[132:135], v[178:181], v[120:123]
	v_mfma_f32_16x16x32_bf16 v[112:115], v[140:143], v[178:181], v[112:115]
	v_mfma_f32_16x16x32_bf16 v[104:107], v[132:135], v[186:189], v[104:107]
	v_mfma_f32_16x16x32_bf16 v[96:99], v[140:143], v[186:189], v[96:99]
	v_mfma_f32_16x16x32_bf16 v[88:91], v[132:135], v[222:225], v[88:91]
	v_mfma_f32_16x16x32_bf16 v[80:83], v[140:143], v[222:225], v[80:83]
	v_mfma_f32_16x16x32_bf16 v[72:75], v[132:135], v[230:233], v[72:75]
	v_mfma_f32_16x16x32_bf16 v[64:67], v[140:143], v[230:233], v[64:67]
	s_setprio 0
	s_setprio 1
	v_mfma_f32_16x16x32_bf16 v[124:127], v[144:147], v[174:177], v[124:127]
	v_mfma_f32_16x16x32_bf16 v[116:119], v[152:155], v[174:177], v[116:119]
	v_mfma_f32_16x16x32_bf16 v[108:111], v[144:147], v[182:185], v[108:111]
	v_mfma_f32_16x16x32_bf16 v[100:103], v[152:155], v[182:185], v[100:103]
	v_mfma_f32_16x16x32_bf16 v[92:95], v[144:147], v[190:193], v[92:95]
	v_mfma_f32_16x16x32_bf16 v[84:87], v[152:155], v[190:193], v[84:87]
	v_mfma_f32_16x16x32_bf16 v[76:79], v[144:147], v[226:229], v[76:79]
	v_mfma_f32_16x16x32_bf16 v[68:71], v[152:155], v[226:229], v[68:71]
	v_mfma_f32_16x16x32_bf16 v[124:127], v[148:151], v[178:181], v[124:127]
	v_mfma_f32_16x16x32_bf16 v[116:119], v[170:173], v[178:181], v[116:119]
	v_mfma_f32_16x16x32_bf16 v[108:111], v[148:151], v[186:189], v[108:111]
	v_mfma_f32_16x16x32_bf16 v[100:103], v[170:173], v[186:189], v[100:103]
	v_mfma_f32_16x16x32_bf16 v[92:95], v[148:151], v[222:225], v[92:95]
	v_mfma_f32_16x16x32_bf16 v[84:87], v[170:173], v[222:225], v[84:87]
	v_mfma_f32_16x16x32_bf16 v[76:79], v[148:151], v[230:233], v[76:79]
	v_mfma_f32_16x16x32_bf16 v[68:71], v[170:173], v[230:233], v[68:71]
	s_setprio 0
	s_barrier
	s_add_i32 s95, s95, s17
	v_lshl_add_u64 v[234:235], s[74:75], 0, v[164:165]
	s_mov_b32 m0, s95
	ds_read_b128 v[174:177], v220 offset:16384
	ds_read_b128 v[178:181], v220 offset:17408
	ds_read_b128 v[182:185], v220 offset:18432
	ds_read_b128 v[186:189], v220 offset:19456
	ds_read_b128 v[190:193], v220 offset:20480
	ds_read_b128 v[222:225], v220 offset:21504
	ds_read_b128 v[226:229], v220 offset:22528
	ds_read_b128 v[230:233], v220 offset:23552
	global_load_lds_dwordx4 v[234:235], off
	s_add_i32 m0, s95, 0x2000
	v_lshl_add_u64 v[236:237], s[74:75], 0, v[160:161]
	s_add_u32 s74, s74, s24
	s_addc_u32 s75, s75, s25
	s_add_i32 s34, s34, s17
	global_load_lds_dwordx4 v[236:237], off
	v_lshl_add_u64 v[238:239], s[74:75], 0, v[164:165]
	s_mov_b32 m0, s34
	v_lshl_add_u64 v[240:241], s[74:75], 0, v[160:161]
	global_load_lds_dwordx4 v[238:239], off
	s_add_i32 m0, s34, 0x2000
	v_lshl_add_u64 v[242:243], s[56:57], 0, v[162:163]
	global_load_lds_dwordx4 v[240:241], off
	s_mov_b32 m0, s44
	v_lshl_add_u64 v[244:245], s[56:57], 0, v[158:159]
	global_load_lds_dwordx4 v[242:243], off
	s_mov_b32 m0, s93
	s_nop 0
	global_load_lds_dwordx4 v[244:245], off
	s_waitcnt vmcnt(8)
	s_waitcnt lgkmcnt(0)
	s_barrier
	s_setprio 1
	s_waitcnt lgkmcnt(0)
	v_mfma_f32_16x16x32_bf16 v[56:59], v[128:131], v[174:177], v[56:59]
	v_mfma_f32_16x16x32_bf16 v[48:51], v[136:139], v[174:177], v[48:51]
	v_mfma_f32_16x16x32_bf16 v[40:43], v[128:131], v[182:185], v[40:43]
	v_mfma_f32_16x16x32_bf16 v[32:35], v[136:139], v[182:185], v[32:35]
	v_mfma_f32_16x16x32_bf16 v[24:27], v[128:131], v[190:193], v[24:27]
	v_mfma_f32_16x16x32_bf16 v[16:19], v[136:139], v[190:193], v[16:19]
	v_mfma_f32_16x16x32_bf16 v[8:11], v[128:131], v[226:229], v[8:11]
	v_mfma_f32_16x16x32_bf16 v[0:3], v[136:139], v[226:229], v[0:3]
	v_mfma_f32_16x16x32_bf16 v[56:59], v[132:135], v[178:181], v[56:59]
	v_mfma_f32_16x16x32_bf16 v[48:51], v[140:143], v[178:181], v[48:51]
	v_mfma_f32_16x16x32_bf16 v[40:43], v[132:135], v[186:189], v[40:43]
	v_mfma_f32_16x16x32_bf16 v[32:35], v[140:143], v[186:189], v[32:35]
	v_mfma_f32_16x16x32_bf16 v[24:27], v[132:135], v[222:225], v[24:27]
	v_mfma_f32_16x16x32_bf16 v[16:19], v[140:143], v[222:225], v[16:19]
	v_mfma_f32_16x16x32_bf16 v[8:11], v[132:135], v[230:233], v[8:11]
	v_mfma_f32_16x16x32_bf16 v[0:3], v[140:143], v[230:233], v[0:3]
	s_setprio 0
	s_setprio 1
	v_mfma_f32_16x16x32_bf16 v[60:63], v[144:147], v[174:177], v[60:63]
	v_mfma_f32_16x16x32_bf16 v[52:55], v[152:155], v[174:177], v[52:55]
	v_mfma_f32_16x16x32_bf16 v[44:47], v[144:147], v[182:185], v[44:47]
	v_mfma_f32_16x16x32_bf16 v[36:39], v[152:155], v[182:185], v[36:39]
	v_mfma_f32_16x16x32_bf16 v[28:31], v[144:147], v[190:193], v[28:31]
	v_mfma_f32_16x16x32_bf16 v[20:23], v[152:155], v[190:193], v[20:23]
	v_mfma_f32_16x16x32_bf16 v[12:15], v[144:147], v[226:229], v[12:15]
	v_mfma_f32_16x16x32_bf16 v[4:7], v[152:155], v[226:229], v[4:7]
	v_mfma_f32_16x16x32_bf16 v[60:63], v[148:151], v[178:181], v[60:63]
	v_mfma_f32_16x16x32_bf16 v[52:55], v[170:173], v[178:181], v[52:55]
	v_mfma_f32_16x16x32_bf16 v[44:47], v[148:151], v[186:189], v[44:47]
	v_mfma_f32_16x16x32_bf16 v[36:39], v[170:173], v[186:189], v[36:39]
	v_mfma_f32_16x16x32_bf16 v[28:31], v[148:151], v[222:225], v[28:31]
	v_mfma_f32_16x16x32_bf16 v[20:23], v[170:173], v[222:225], v[20:23]
	v_mfma_f32_16x16x32_bf16 v[12:15], v[148:151], v[230:233], v[12:15]
	v_mfma_f32_16x16x32_bf16 v[4:7], v[170:173], v[230:233], v[4:7]
	s_setprio 0
	s_barrier
	s_add_i32 s34, 0, 0x18000
	s_add_i32 s74, 0, 0x1c000
	v_add_u32_e32 v140, s34, v217
	v_add_u32_e32 v156, s74, v217
	ds_read_b128 v[128:131], v140
	ds_read_b128 v[132:135], v140 offset:1024
	ds_read_b128 v[136:139], v140 offset:2048
	ds_read_b128 v[140:143], v140 offset:3072
	ds_read_b128 v[144:147], v156
	ds_read_b128 v[148:151], v156 offset:1024
	ds_read_b128 v[152:155], v156 offset:2048
	ds_read_b128 v[170:173], v156 offset:3072
	s_add_u32 s56, s56, s24
	s_addc_u32 s57, s57, s25
	s_mov_b32 m0, s8
	v_lshl_add_u64 v[246:247], s[56:57], 0, v[162:163]
	ds_read_b128 v[174:177], v220 offset:32768
	ds_read_b128 v[178:181], v220 offset:33792
	ds_read_b128 v[182:185], v220 offset:34816
	ds_read_b128 v[186:189], v220 offset:35840
	ds_read_b128 v[190:193], v220 offset:36864
	ds_read_b128 v[222:225], v220 offset:37888
	ds_read_b128 v[226:229], v220 offset:38912
	ds_read_b128 v[230:233], v220 offset:39936
	global_load_lds_dwordx4 v[246:247], off
	v_lshl_add_u64 v[246:247], s[56:57], 0, v[158:159]
	s_mov_b32 m0, s55
	s_nop 0
	global_load_lds_dwordx4 v[246:247], off
	s_waitcnt vmcnt(8)
	s_waitcnt lgkmcnt(0)
	s_barrier
	s_setprio 1
	s_waitcnt lgkmcnt(0)
	v_mfma_f32_16x16x32_bf16 v[120:123], v[128:131], v[174:177], v[120:123]
	v_mfma_f32_16x16x32_bf16 v[112:115], v[136:139], v[174:177], v[112:115]
	v_mfma_f32_16x16x32_bf16 v[104:107], v[128:131], v[182:185], v[104:107]
	v_mfma_f32_16x16x32_bf16 v[96:99], v[136:139], v[182:185], v[96:99]
	v_mfma_f32_16x16x32_bf16 v[88:91], v[128:131], v[190:193], v[88:91]
	v_mfma_f32_16x16x32_bf16 v[80:83], v[136:139], v[190:193], v[80:83]
	v_mfma_f32_16x16x32_bf16 v[72:75], v[128:131], v[226:229], v[72:75]
	v_mfma_f32_16x16x32_bf16 v[64:67], v[136:139], v[226:229], v[64:67]
	v_mfma_f32_16x16x32_bf16 v[120:123], v[132:135], v[178:181], v[120:123]
	v_mfma_f32_16x16x32_bf16 v[112:115], v[140:143], v[178:181], v[112:115]
	v_mfma_f32_16x16x32_bf16 v[104:107], v[132:135], v[186:189], v[104:107]
	v_mfma_f32_16x16x32_bf16 v[96:99], v[140:143], v[186:189], v[96:99]
	v_mfma_f32_16x16x32_bf16 v[88:91], v[132:135], v[222:225], v[88:91]
	v_mfma_f32_16x16x32_bf16 v[80:83], v[140:143], v[222:225], v[80:83]
	v_mfma_f32_16x16x32_bf16 v[72:75], v[132:135], v[230:233], v[72:75]
	v_mfma_f32_16x16x32_bf16 v[64:67], v[140:143], v[230:233], v[64:67]
	s_setprio 0
	s_setprio 1
	v_mfma_f32_16x16x32_bf16 v[124:127], v[144:147], v[174:177], v[124:127]
	v_mfma_f32_16x16x32_bf16 v[116:119], v[152:155], v[174:177], v[116:119]
	v_mfma_f32_16x16x32_bf16 v[108:111], v[144:147], v[182:185], v[108:111]
	v_mfma_f32_16x16x32_bf16 v[100:103], v[152:155], v[182:185], v[100:103]
	v_mfma_f32_16x16x32_bf16 v[92:95], v[144:147], v[190:193], v[92:95]
	v_mfma_f32_16x16x32_bf16 v[84:87], v[152:155], v[190:193], v[84:87]
	v_mfma_f32_16x16x32_bf16 v[76:79], v[144:147], v[226:229], v[76:79]
	v_mfma_f32_16x16x32_bf16 v[68:71], v[152:155], v[226:229], v[68:71]
	v_mfma_f32_16x16x32_bf16 v[124:127], v[148:151], v[178:181], v[124:127]
	v_mfma_f32_16x16x32_bf16 v[116:119], v[170:173], v[178:181], v[116:119]
	v_mfma_f32_16x16x32_bf16 v[108:111], v[148:151], v[186:189], v[108:111]
	v_mfma_f32_16x16x32_bf16 v[100:103], v[170:173], v[186:189], v[100:103]
	v_mfma_f32_16x16x32_bf16 v[92:95], v[148:151], v[222:225], v[92:95]
	v_mfma_f32_16x16x32_bf16 v[84:87], v[170:173], v[222:225], v[84:87]
	v_mfma_f32_16x16x32_bf16 v[76:79], v[148:151], v[230:233], v[76:79]
	v_mfma_f32_16x16x32_bf16 v[68:71], v[170:173], v[230:233], v[68:71]
	s_setprio 0
	s_barrier
	s_add_i32 s34, s34, s17
	v_lshl_add_u64 v[234:235], v[234:235], 0, s[52:53]
	s_mov_b32 m0, s34
	ds_read_b128 v[174:177], v220 offset:49152
	ds_read_b128 v[178:181], v220 offset:50176
	ds_read_b128 v[182:185], v220 offset:51200
	ds_read_b128 v[186:189], v220 offset:52224
	ds_read_b128 v[190:193], v220 offset:53248
	ds_read_b128 v[222:225], v220 offset:54272
	ds_read_b128 v[226:229], v220 offset:55296
	ds_read_b128 v[230:233], v220 offset:56320
	global_load_lds_dwordx4 v[234:235], off
	v_lshl_add_u64 v[234:235], v[236:237], 0, s[52:53]
	s_add_i32 m0, s34, 0x2000
	s_add_i32 s34, s74, s17
	global_load_lds_dwordx4 v[234:235], off
	v_lshl_add_u64 v[234:235], v[238:239], 0, s[52:53]
	s_mov_b32 m0, s34
	s_nop 0
	global_load_lds_dwordx4 v[234:235], off
	v_lshl_add_u64 v[234:235], v[240:241], 0, s[52:53]
	s_add_i32 m0, s34, 0x2000
	s_nop 0
	global_load_lds_dwordx4 v[234:235], off
	v_lshl_add_u64 v[234:235], v[242:243], 0, s[52:53]
	s_mov_b32 m0, s9
	s_nop 0
	global_load_lds_dwordx4 v[234:235], off
	v_lshl_add_u64 v[234:235], v[244:245], 0, s[52:53]
	s_mov_b32 m0, s29
	s_nop 0
	global_load_lds_dwordx4 v[234:235], off
	s_waitcnt vmcnt(8)
	s_waitcnt lgkmcnt(0)
	s_barrier
	s_cmp_ge_i32 s35, s49
	s_cbranch_scc0 .Lpf_skip
	s_cmp_eq_u32 s47, 0
	s_cbranch_scc1 .Lpf_do
	s_cmp_eq_u32 s47, 1
	s_cbranch_scc0 .Lpf_skip
	s_cmp_eq_u64 s[96:97], 0
	s_cbranch_scc1 .Lpf_skip
.Lpf_do:
	v_add_u32_e32 v246, s92, v216
	v_lshl_add_u32 v246, s15, 8, v246
	v_ashrrev_i32_e32 v247, 31, v246
	v_lshl_add_u64 v[246:247], v[246:247], 3, s[96:97]
	global_load_dwordx2 v[234:235], v[246:247], off
	global_load_dwordx2 v[236:237], v[246:247], off offset:128
	global_load_dwordx2 v[238:239], v[246:247], off offset:256
	global_load_dwordx2 v[240:241], v[246:247], off offset:384
	global_load_dwordx2 v[242:243], v[246:247], off offset:1024
	global_load_dwordx2 v[244:245], v[246:247], off offset:1152
	global_load_dwordx2 v[250:251], v[246:247], off offset:1280
	global_load_dwordx2 v[252:253], v[246:247], off offset:1408
.Lpf_skip:
	s_setprio 1
	s_waitcnt lgkmcnt(0)
	v_mfma_f32_16x16x32_bf16 v[56:59], v[128:131], v[174:177], v[56:59]
	v_mfma_f32_16x16x32_bf16 v[48:51], v[136:139], v[174:177], v[48:51]
	v_mfma_f32_16x16x32_bf16 v[40:43], v[128:131], v[182:185], v[40:43]
	v_mfma_f32_16x16x32_bf16 v[32:35], v[136:139], v[182:185], v[32:35]
	v_mfma_f32_16x16x32_bf16 v[24:27], v[128:131], v[190:193], v[24:27]
	v_mfma_f32_16x16x32_bf16 v[16:19], v[136:139], v[190:193], v[16:19]
	v_mfma_f32_16x16x32_bf16 v[8:11], v[128:131], v[226:229], v[8:11]
	v_mfma_f32_16x16x32_bf16 v[0:3], v[136:139], v[226:229], v[0:3]
	v_mfma_f32_16x16x32_bf16 v[56:59], v[132:135], v[178:181], v[56:59]
	v_mfma_f32_16x16x32_bf16 v[48:51], v[140:143], v[178:181], v[48:51]
	v_mfma_f32_16x16x32_bf16 v[40:43], v[132:135], v[186:189], v[40:43]
	v_mfma_f32_16x16x32_bf16 v[32:35], v[140:143], v[186:189], v[32:35]
	v_mfma_f32_16x16x32_bf16 v[24:27], v[132:135], v[222:225], v[24:27]
	v_mfma_f32_16x16x32_bf16 v[16:19], v[140:143], v[222:225], v[16:19]
	v_mfma_f32_16x16x32_bf16 v[8:11], v[132:135], v[230:233], v[8:11]
	v_mfma_f32_16x16x32_bf16 v[0:3], v[140:143], v[230:233], v[0:3]
	s_setprio 0
	s_setprio 1
	v_mfma_f32_16x16x32_bf16 v[60:63], v[144:147], v[174:177], v[60:63]
	v_mfma_f32_16x16x32_bf16 v[52:55], v[152:155], v[174:177], v[52:55]
	v_mfma_f32_16x16x32_bf16 v[44:47], v[144:147], v[182:185], v[44:47]
	v_mfma_f32_16x16x32_bf16 v[36:39], v[152:155], v[182:185], v[36:39]
	v_mfma_f32_16x16x32_bf16 v[28:31], v[144:147], v[190:193], v[28:31]
	v_mfma_f32_16x16x32_bf16 v[20:23], v[152:155], v[190:193], v[20:23]
	v_mfma_f32_16x16x32_bf16 v[12:15], v[144:147], v[226:229], v[12:15]
	v_mfma_f32_16x16x32_bf16 v[4:7], v[152:155], v[226:229], v[4:7]
	v_mfma_f32_16x16x32_bf16 v[60:63], v[148:151], v[178:181], v[60:63]
	v_mfma_f32_16x16x32_bf16 v[52:55], v[170:173], v[178:181], v[52:55]
	v_mfma_f32_16x16x32_bf16 v[44:47], v[148:151], v[186:189], v[44:47]
	v_mfma_f32_16x16x32_bf16 v[36:39], v[170:173], v[186:189], v[36:39]
	v_mfma_f32_16x16x32_bf16 v[28:31], v[148:151], v[222:225], v[28:31]
	v_mfma_f32_16x16x32_bf16 v[20:23], v[170:173], v[222:225], v[20:23]
	v_mfma_f32_16x16x32_bf16 v[12:15], v[148:151], v[230:233], v[12:15]
	v_mfma_f32_16x16x32_bf16 v[4:7], v[170:173], v[230:233], v[4:7]
	s_setprio 0
	s_barrier
	s_add_u32 s6, s6, 0x100
	s_addc_u32 s7, s7, 0
	s_add_u32 s1, s1, 0x100
	s_addc_u32 s2, s2, 0
	s_cmp_ge_i32 s35, s49
	s_mov_b32 s34, s35
	s_cbranch_scc0 .LBB0_625

.LBB0_653:
	s_and_b64 vcc, exec, s[6:7]
	s_cbranch_vccz .LBB0_674
	s_cmp_gt_i32 s47, 0
	s_mov_b64 s[6:7], -1
	s_cbranch_scc0 .LBB0_672
	s_lshl_b32 s1, s15, 8
	v_add_u32_e32 v134, s1, v170
	v_ashrrev_i32_e32 v135, 31, v134
	v_mov_b32_e32 v132, 0x358637bd
	v_mov_b32_e32 v142, 0x358637bd
	v_mov_b32_e32 v143, 0x358637bd
	v_mov_b32_e32 v141, 0x358637bd
	v_mov_b32_e32 v139, 0x358637bd
	v_mov_b32_e32 v140, 0x358637bd
	v_mov_b32_e32 v131, 0x358637bd
	v_mov_b32_e32 v137, 0x358637bd
	v_add_u32_e32 v138, 0x80, v134
	v_add_u32_e32 v136, 0x90, v134
	v_add_u32_e32 v130, 0xa0, v134
	v_add_u32_e32 v128, 0xb0, v134
	v_ashrrev_i32_e32 v129, 31, v128
	s_andn2_b64 vcc, exec, s[64:65]
	s_waitcnt lgkmcnt(0)
	s_cbranch_vccnz .LBB0_671
	s_flbit_i32_b32 s1, 0
	s_min_u32 s2, s1, 32
	s_sub_i32 s1, 32, s2
	s_waitcnt vmcnt(0)
	v_mov_b32_e32 v156, v235
	v_lshlrev_b64 v[144:145], s2, v[156:157]
	v_min_u32_e32 v146, 1, v144
	v_or_b32_e32 v146, v145, v146
	v_cvt_f32_u32_e32 v146, v146
	v_cvt_f32_u32_e32 v147, v234
	v_ldexp_f32 v146, v146, s1
	v_mul_f32_e32 v146, 0x43800000, v146
	v_fmac_f32_e32 v146, 0x33800000, v147
	v_fmamk_f32 v132, v146, 0x3a800000, v194
	v_mov_b32_e32 v156, v237
	v_lshlrev_b64 v[144:145], s2, v[156:157]
	v_min_u32_e32 v146, 1, v144
	v_or_b32_e32 v146, v145, v146
	v_cvt_f32_u32_e32 v146, v146
	v_cvt_f32_u32_e32 v147, v236
	v_ldexp_f32 v146, v146, s1
	v_mul_f32_e32 v146, 0x43800000, v146
	v_fmac_f32_e32 v146, 0x33800000, v147
	v_fmamk_f32 v142, v146, 0x3a800000, v194
	v_mov_b32_e32 v156, v239
	v_lshlrev_b64 v[144:145], s2, v[156:157]
	v_min_u32_e32 v146, 1, v144
	v_or_b32_e32 v146, v145, v146
	v_cvt_f32_u32_e32 v146, v146
	v_cvt_f32_u32_e32 v147, v238
	v_ldexp_f32 v146, v146, s1
	v_mul_f32_e32 v146, 0x43800000, v146
	v_fmac_f32_e32 v146, 0x33800000, v147
	v_fmamk_f32 v143, v146, 0x3a800000, v194
	v_mov_b32_e32 v156, v241
	v_lshlrev_b64 v[144:145], s2, v[156:157]
	v_min_u32_e32 v146, 1, v144
	v_or_b32_e32 v146, v145, v146
	v_cvt_f32_u32_e32 v146, v146
	v_cvt_f32_u32_e32 v147, v240
	v_ldexp_f32 v146, v146, s1
	v_mul_f32_e32 v146, 0x43800000, v146
	v_fmac_f32_e32 v146, 0x33800000, v147
	v_fmamk_f32 v141, v146, 0x3a800000, v194
	v_mov_b32_e32 v156, v243
	v_lshlrev_b64 v[144:145], s2, v[156:157]
	v_min_u32_e32 v146, 1, v144
	v_or_b32_e32 v146, v145, v146
	v_cvt_f32_u32_e32 v146, v146
	v_cvt_f32_u32_e32 v147, v242
	v_ldexp_f32 v146, v146, s1
	v_mul_f32_e32 v146, 0x43800000, v146
	v_fmac_f32_e32 v146, 0x33800000, v147
	v_fmamk_f32 v139, v146, 0x3a800000, v194
	v_mov_b32_e32 v156, v245
	v_lshlrev_b64 v[144:145], s2, v[156:157]
	v_min_u32_e32 v146, 1, v144
	v_or_b32_e32 v146, v145, v146
	v_cvt_f32_u32_e32 v146, v146
	v_cvt_f32_u32_e32 v147, v244
	v_ldexp_f32 v146, v146, s1
	v_mul_f32_e32 v146, 0x43800000, v146
	v_fmac_f32_e32 v146, 0x33800000, v147
	v_fmamk_f32 v140, v146, 0x3a800000, v194
	v_mov_b32_e32 v156, v251
	v_lshlrev_b64 v[144:145], s2, v[156:157]
	v_min_u32_e32 v146, 1, v144
	v_or_b32_e32 v146, v145, v146
	v_cvt_f32_u32_e32 v146, v146
	v_cvt_f32_u32_e32 v147, v250
	v_ldexp_f32 v146, v146, s1
	v_mul_f32_e32 v146, 0x43800000, v146
	v_fmac_f32_e32 v146, 0x33800000, v147
	v_fmamk_f32 v131, v146, 0x3a800000, v194
	v_mov_b32_e32 v156, v253
	v_lshlrev_b64 v[144:145], s2, v[156:157]
	v_min_u32_e32 v146, 1, v144
	v_or_b32_e32 v146, v145, v146
	v_cvt_f32_u32_e32 v146, v146
	v_cvt_f32_u32_e32 v147, v252
	v_ldexp_f32 v146, v146, s1
	v_mul_f32_e32 v146, 0x43800000, v146
	v_fmac_f32_e32 v146, 0x33800000, v147
	v_fmamk_f32 v137, v146, 0x3a800000, v194

.LBB0_741:
	s_and_b64 vcc, exec, s[56:57]
	s_cbranch_vccz .LBB0_740
	v_lshl_add_u32 v144, s15, 8, v170
	v_ashrrev_i32_e32 v145, 31, v144
	s_waitcnt lgkmcnt(0)
	s_flbit_i32_b32 s1, 0
	s_min_u32 s2, s1, 32
	s_sub_i32 s1, 32, s2
	v_add_u32_e32 v142, 16, v144
	v_ashrrev_i32_e32 v143, 31, v142
	v_add_u32_e32 v140, 32, v144
	v_ashrrev_i32_e32 v141, 31, v140
	v_add_u32_e32 v138, 48, v144
	v_ashrrev_i32_e32 v139, 31, v138
	v_add_u32_e32 v136, 0x80, v144
	v_ashrrev_i32_e32 v137, 31, v136
	v_add_u32_e32 v134, 0x90, v144
	v_ashrrev_i32_e32 v135, 31, v134
	v_pk_mul_f32 v[126:127], v[126:127], v[122:123]
	v_pk_mul_f32 v[118:119], v[118:119], v[114:115]
	v_pk_mul_f32 v[110:111], v[110:111], v[106:107]
	v_pk_mul_f32 v[102:103], v[102:103], v[98:99]
	v_pk_mul_f32 v[94:95], v[94:95], v[90:91]
	v_pk_mul_f32 v[86:87], v[86:87], v[82:83]
	v_pk_mul_f32 v[78:79], v[78:79], v[74:75]
	v_pk_mul_f32 v[70:71], v[70:71], v[66:67]
	v_pk_mul_f32 v[62:63], v[62:63], v[58:59]
	v_pk_mul_f32 v[54:55], v[54:55], v[50:51]
	v_pk_mul_f32 v[46:47], v[46:47], v[42:43]
	v_pk_mul_f32 v[38:39], v[38:39], v[34:35]
	v_pk_mul_f32 v[30:31], v[30:31], v[26:27]
	v_pk_mul_f32 v[22:23], v[22:23], v[18:19]
	v_pk_mul_f32 v[14:15], v[14:15], v[10:11]
	v_pk_mul_f32 v[6:7], v[6:7], v[2:3]
	s_waitcnt vmcnt(0)
	v_mov_b32_e32 v156, v235
	v_lshlrev_b64 v[130:131], s2, v[156:157]
	v_min_u32_e32 v129, 1, v130
	v_or_b32_e32 v129, v131, v129
	v_cvt_f32_u32_e32 v129, v129
	v_cvt_f32_u32_e32 v128, v234
	v_ldexp_f32 v129, v129, s1
	v_mul_f32_e32 v153, 0x43800000, v129
	v_fmac_f32_e32 v153, 0x33800000, v128
	v_fmamk_f32 v153, v153, 0x3a800000, v194
	v_rsq_f32_e32 v153, v153
	v_mov_b32_e32 v156, v237
	v_lshlrev_b64 v[130:131], s2, v[156:157]
	v_min_u32_e32 v129, 1, v130
	v_or_b32_e32 v129, v131, v129
	v_cvt_f32_u32_e32 v129, v129
	v_cvt_f32_u32_e32 v128, v236
	v_ldexp_f32 v129, v129, s1
	v_mul_f32_e32 v152, 0x43800000, v129
	v_fmac_f32_e32 v152, 0x33800000, v128
	v_mov_b32_e32 v156, v239
	v_lshlrev_b64 v[130:131], s2, v[156:157]
	v_min_u32_e32 v129, 1, v130
	v_or_b32_e32 v129, v131, v129
	v_cvt_f32_u32_e32 v129, v129
	v_cvt_f32_u32_e32 v128, v238
	v_ldexp_f32 v129, v129, s1
	v_mul_f32_e32 v151, 0x43800000, v129
	v_fmac_f32_e32 v151, 0x33800000, v128
	v_mov_b32_e32 v156, v241
	v_lshlrev_b64 v[130:131], s2, v[156:157]
	v_min_u32_e32 v129, 1, v130
	v_or_b32_e32 v129, v131, v129
	v_cvt_f32_u32_e32 v129, v129
	v_cvt_f32_u32_e32 v128, v240
	v_ldexp_f32 v129, v129, s1
	v_mul_f32_e32 v150, 0x43800000, v129
	v_fmac_f32_e32 v150, 0x33800000, v128
	v_mov_b32_e32 v156, v243
	v_lshlrev_b64 v[130:131], s2, v[156:157]
	v_min_u32_e32 v129, 1, v130
	v_or_b32_e32 v129, v131, v129
	v_cvt_f32_u32_e32 v129, v129
	v_cvt_f32_u32_e32 v128, v242
	v_ldexp_f32 v129, v129, s1
	v_mul_f32_e32 v149, 0x43800000, v129
	v_fmac_f32_e32 v149, 0x33800000, v128
	v_mov_b32_e32 v156, v245
	v_lshlrev_b64 v[130:131], s2, v[156:157]
	v_min_u32_e32 v129, 1, v130
	v_or_b32_e32 v129, v131, v129
	v_cvt_f32_u32_e32 v129, v129
	v_cvt_f32_u32_e32 v128, v244
	v_ldexp_f32 v129, v129, s1
	v_mul_f32_e32 v148, 0x43800000, v129
	v_fmac_f32_e32 v148, 0x33800000, v128
	v_mov_b32_e32 v156, v251
	v_lshlrev_b64 v[130:131], s2, v[156:157]
	v_min_u32_e32 v129, 1, v130
	v_or_b32_e32 v129, v131, v129
	v_cvt_f32_u32_e32 v129, v129
	v_cvt_f32_u32_e32 v128, v250
	v_ldexp_f32 v129, v129, s1
	v_mul_f32_e32 v146, 0x43800000, v129
	v_fmac_f32_e32 v146, 0x33800000, v128
	v_mov_b32_e32 v132, v252
	v_mov_b32_e32 v133, v253
	v_add_u32_e32 v130, 0xa0, v144
	v_ashrrev_i32_e32 v131, 31, v130
	v_add_u32_e32 v128, 0xb0, v144
	v_ashrrev_i32_e32 v129, 31, v128
	v_mov_b32_e32 v156, v133
	v_lshlrev_b64 v[154:155], s2, v[156:157]
	v_min_u32_e32 v133, 1, v154
	v_mul_f32_e32 v154, 0xbfb8aa3b, v153
	v_pk_mul_f32 v[170:171], v[120:121], v[154:155] op_sel_hi:[1,0]
	v_pk_mul_f32 v[122:123], v[122:123], v[154:155] op_sel_hi:[1,0]
	v_exp_f32_e32 v170, v170
	v_exp_f32_e32 v171, v171
	v_exp_f32_e32 v122, v122
	v_exp_f32_e32 v123, v123
	v_mul_f32_e32 v156, v153, v153
	v_pk_add_f32 v[170:171], v[170:171], 1.0 op_sel_hi:[1,0]
	v_pk_mul_f32 v[120:121], v[124:125], v[120:121]
	v_pk_add_f32 v[122:123], v[122:123], 1.0 op_sel_hi:[1,0]
	v_rcp_f32_e32 v170, v170
	v_rcp_f32_e32 v171, v171
	v_rcp_f32_e32 v122, v122
	v_rcp_f32_e32 v123, v123
	v_or_b32_e32 v133, v155, v133
	v_pk_mul_f32 v[124:125], v[156:157], v[170:171] op_sel_hi:[0,1]
	v_pk_mul_f32 v[120:121], v[120:121], v[124:125]
	v_pk_mul_f32 v[122:123], v[156:157], v[122:123] op_sel_hi:[0,1]
	v_pk_mul_f32 v[122:123], v[126:127], v[122:123]
	v_cvt_pk_bf16_f32 v120, v120, v121
	v_cvt_f32_u32_e32 v133, v133
	v_cvt_pk_bf16_f32 v121, v122, v123
	v_pk_mul_f32 v[122:123], v[112:113], v[154:155] op_sel_hi:[1,0]
	v_pk_mul_f32 v[112:113], v[116:117], v[112:113]
	v_exp_f32_e32 v122, v122
	v_exp_f32_e32 v123, v123
	v_cvt_f32_u32_e32 v132, v132
	v_ldexp_f32 v133, v133, s1
	s_lshl_b32 s1, s48, 7
	v_pk_add_f32 v[122:123], v[122:123], 1.0 op_sel_hi:[1,0]
	v_mul_f32_e32 v147, 0x43800000, v133
	v_rcp_f32_e32 v122, v122
	v_rcp_f32_e32 v123, v123
	s_or_b32 s1, s1, s58
	v_fmac_f32_e32 v147, 0x33800000, v132
	v_lshl_add_u32 v132, v221, 3, s1
	v_pk_mul_f32 v[116:117], v[156:157], v[122:123] op_sel_hi:[0,1]
	v_pk_mul_f32 v[112:113], v[112:113], v[116:117]
	v_ashrrev_i32_e32 v133, 31, v132
	v_cvt_pk_bf16_f32 v122, v112, v113
	v_pk_mul_f32 v[112:113], v[114:115], v[154:155] op_sel_hi:[1,0]
	v_lshl_add_u64 v[132:133], v[132:133], 1, s[76:77]
	v_exp_f32_e32 v112, v112
	v_exp_f32_e32 v113, v113
	s_nop 0
	v_pk_add_f32 v[112:113], v[112:113], 1.0 op_sel_hi:[1,0]
	s_nop 0
	v_rcp_f32_e32 v112, v112
	v_rcp_f32_e32 v113, v113
	s_nop 0
	v_pk_mul_f32 v[112:113], v[156:157], v[112:113] op_sel_hi:[0,1]
	v_pk_mul_f32 v[112:113], v[118:119], v[112:113]
	s_nop 0
	v_cvt_pk_bf16_f32 v123, v112, v113
	v_mad_u64_u32 v[112:113], s[6:7], v144, s14, 0
	v_mov_b32_e32 v114, v113
	v_mad_u64_u32 v[114:115], s[6:7], v145, s14, v[114:115]
	v_mov_b32_e32 v113, v114
	v_lshl_add_u64 v[112:113], v[112:113], 1, v[132:133]
	global_store_dwordx4 v[112:113], v[120:123], off
	v_fmamk_f32 v112, v152, 0x3a800000, v194
	v_rsq_f32_e32 v113, v112
	s_nop 0
	v_mul_f32_e32 v112, 0xbfb8aa3b, v113
	v_pk_mul_f32 v[116:117], v[104:105], v[112:113] op_sel_hi:[1,0]
	v_pk_mul_f32 v[106:107], v[106:107], v[112:113] op_sel_hi:[1,0]
	v_exp_f32_e32 v116, v116
	v_exp_f32_e32 v117, v117
	v_exp_f32_e32 v106, v106
	v_exp_f32_e32 v107, v107
	v_mul_f32_e32 v114, v113, v113
	v_pk_add_f32 v[116:117], v[116:117], 1.0 op_sel_hi:[1,0]
	v_pk_mul_f32 v[104:105], v[108:109], v[104:105]
	v_pk_add_f32 v[106:107], v[106:107], 1.0 op_sel_hi:[1,0]
	v_rcp_f32_e32 v116, v116
	v_rcp_f32_e32 v117, v117
	v_rcp_f32_e32 v106, v106
	v_rcp_f32_e32 v107, v107
	v_pk_mul_f32 v[108:109], v[114:115], v[116:117] op_sel_hi:[0,1]
	v_pk_mul_f32 v[104:105], v[104:105], v[108:109]
	v_pk_mul_f32 v[106:107], v[114:115], v[106:107] op_sel_hi:[0,1]
	v_pk_mul_f32 v[106:107], v[110:111], v[106:107]
	v_cvt_pk_bf16_f32 v104, v104, v105
	s_nop 0
	v_cvt_pk_bf16_f32 v105, v106, v107
	v_pk_mul_f32 v[106:107], v[96:97], v[112:113] op_sel_hi:[1,0]
	v_pk_mul_f32 v[96:97], v[100:101], v[96:97]
	v_exp_f32_e32 v106, v106
	v_exp_f32_e32 v107, v107
	s_nop 0
	v_pk_add_f32 v[106:107], v[106:107], 1.0 op_sel_hi:[1,0]
	s_nop 0
	v_rcp_f32_e32 v106, v106
	v_rcp_f32_e32 v107, v107
	s_nop 0
	v_pk_mul_f32 v[100:101], v[114:115], v[106:107] op_sel_hi:[0,1]
	v_pk_mul_f32 v[96:97], v[96:97], v[100:101]
	s_nop 0
	v_cvt_pk_bf16_f32 v106, v96, v97
	v_pk_mul_f32 v[96:97], v[98:99], v[112:113] op_sel_hi:[1,0]
	s_nop 0
	v_exp_f32_e32 v96, v96
	v_exp_f32_e32 v97, v97
	s_nop 0
	v_pk_add_f32 v[96:97], v[96:97], 1.0 op_sel_hi:[1,0]
	s_nop 0
	v_rcp_f32_e32 v96, v96
	v_rcp_f32_e32 v97, v97
	s_nop 0
	v_pk_mul_f32 v[96:97], v[114:115], v[96:97] op_sel_hi:[0,1]
	v_pk_mul_f32 v[96:97], v[102:103], v[96:97]
	s_nop 0
	v_cvt_pk_bf16_f32 v107, v96, v97
	v_mad_u64_u32 v[96:97], s[6:7], v142, s14, 0
	v_mov_b32_e32 v98, v97
	v_mad_u64_u32 v[98:99], s[6:7], v143, s14, v[98:99]
	v_mov_b32_e32 v97, v98
	v_lshl_add_u64 v[96:97], v[96:97], 1, v[132:133]
	global_store_dwordx4 v[96:97], v[104:107], off
	v_fmamk_f32 v96, v151, 0x3a800000, v194
	v_rsq_f32_e32 v97, v96
	s_nop 0
	v_mul_f32_e32 v96, 0xbfb8aa3b, v97
	v_pk_mul_f32 v[100:101], v[88:89], v[96:97] op_sel_hi:[1,0]
	v_pk_mul_f32 v[90:91], v[90:91], v[96:97] op_sel_hi:[1,0]
	v_exp_f32_e32 v100, v100
	v_exp_f32_e32 v101, v101
	v_exp_f32_e32 v90, v90
	v_exp_f32_e32 v91, v91
	v_mul_f32_e32 v98, v97, v97
	v_pk_add_f32 v[100:101], v[100:101], 1.0 op_sel_hi:[1,0]
	v_pk_mul_f32 v[88:89], v[92:93], v[88:89]
	v_pk_add_f32 v[90:91], v[90:91], 1.0 op_sel_hi:[1,0]
	v_rcp_f32_e32 v100, v100
	v_rcp_f32_e32 v101, v101
	v_rcp_f32_e32 v90, v90
	v_rcp_f32_e32 v91, v91
	v_pk_mul_f32 v[92:93], v[98:99], v[100:101] op_sel_hi:[0,1]
	v_pk_mul_f32 v[88:89], v[88:89], v[92:93]
	v_pk_mul_f32 v[90:91], v[98:99], v[90:91] op_sel_hi:[0,1]
	v_pk_mul_f32 v[90:91], v[94:95], v[90:91]
	v_cvt_pk_bf16_f32 v88, v88, v89
	s_nop 0
	v_cvt_pk_bf16_f32 v89, v90, v91
	v_pk_mul_f32 v[90:91], v[80:81], v[96:97] op_sel_hi:[1,0]
	v_pk_mul_f32 v[80:81], v[84:85], v[80:81]
	v_exp_f32_e32 v90, v90
	v_exp_f32_e32 v91, v91
	s_nop 0
	v_pk_add_f32 v[90:91], v[90:91], 1.0 op_sel_hi:[1,0]
	s_nop 0
	v_rcp_f32_e32 v90, v90
	v_rcp_f32_e32 v91, v91
	s_nop 0
	v_pk_mul_f32 v[84:85], v[98:99], v[90:91] op_sel_hi:[0,1]
	v_pk_mul_f32 v[80:81], v[80:81], v[84:85]
	s_nop 0
	v_cvt_pk_bf16_f32 v90, v80, v81
	v_pk_mul_f32 v[80:81], v[82:83], v[96:97] op_sel_hi:[1,0]
	s_nop 0
	v_exp_f32_e32 v80, v80
	v_exp_f32_e32 v81, v81
	s_nop 0
	v_pk_add_f32 v[80:81], v[80:81], 1.0 op_sel_hi:[1,0]
	s_nop 0
	v_rcp_f32_e32 v80, v80
	v_rcp_f32_e32 v81, v81
	s_nop 0
	v_pk_mul_f32 v[80:81], v[98:99], v[80:81] op_sel_hi:[0,1]
	v_pk_mul_f32 v[80:81], v[86:87], v[80:81]
	s_nop 0
	v_cvt_pk_bf16_f32 v91, v80, v81
	v_mad_u64_u32 v[80:81], s[6:7], v140, s14, 0
	v_mov_b32_e32 v82, v81
	v_mad_u64_u32 v[82:83], s[6:7], v141, s14, v[82:83]
	v_mov_b32_e32 v81, v82
	v_lshl_add_u64 v[80:81], v[80:81], 1, v[132:133]
	global_store_dwordx4 v[80:81], v[88:91], off
	v_fmamk_f32 v80, v150, 0x3a800000, v194
	v_rsq_f32_e32 v81, v80
	s_nop 0
	v_mul_f32_e32 v80, 0xbfb8aa3b, v81
	v_pk_mul_f32 v[84:85], v[72:73], v[80:81] op_sel_hi:[1,0]
	v_pk_mul_f32 v[74:75], v[74:75], v[80:81] op_sel_hi:[1,0]
	v_exp_f32_e32 v84, v84
	v_exp_f32_e32 v85, v85
	v_exp_f32_e32 v74, v74
	v_exp_f32_e32 v75, v75
	v_mul_f32_e32 v82, v81, v81
	v_pk_add_f32 v[84:85], v[84:85], 1.0 op_sel_hi:[1,0]
	v_pk_mul_f32 v[72:73], v[76:77], v[72:73]
	v_pk_add_f32 v[74:75], v[74:75], 1.0 op_sel_hi:[1,0]
	v_rcp_f32_e32 v84, v84
	v_rcp_f32_e32 v85, v85
	v_rcp_f32_e32 v74, v74
	v_rcp_f32_e32 v75, v75
	v_pk_mul_f32 v[76:77], v[82:83], v[84:85] op_sel_hi:[0,1]
	v_pk_mul_f32 v[72:73], v[72:73], v[76:77]
	v_pk_mul_f32 v[74:75], v[82:83], v[74:75] op_sel_hi:[0,1]
	v_pk_mul_f32 v[74:75], v[78:79], v[74:75]
	v_cvt_pk_bf16_f32 v72, v72, v73
	s_nop 0
	v_cvt_pk_bf16_f32 v73, v74, v75
	v_pk_mul_f32 v[74:75], v[64:65], v[80:81] op_sel_hi:[1,0]
	v_pk_mul_f32 v[64:65], v[68:69], v[64:65]
	v_exp_f32_e32 v74, v74
	v_exp_f32_e32 v75, v75
	s_nop 0
	v_pk_add_f32 v[74:75], v[74:75], 1.0 op_sel_hi:[1,0]
	s_nop 0
	v_rcp_f32_e32 v74, v74
	v_rcp_f32_e32 v75, v75
	s_nop 0
	v_pk_mul_f32 v[68:69], v[82:83], v[74:75] op_sel_hi:[0,1]
	v_pk_mul_f32 v[64:65], v[64:65], v[68:69]
	s_nop 0
	v_cvt_pk_bf16_f32 v74, v64, v65
	v_pk_mul_f32 v[64:65], v[66:67], v[80:81] op_sel_hi:[1,0]
	s_nop 0
	v_exp_f32_e32 v64, v64
	v_exp_f32_e32 v65, v65
	s_nop 0
	v_pk_add_f32 v[64:65], v[64:65], 1.0 op_sel_hi:[1,0]
	s_nop 0
	v_rcp_f32_e32 v64, v64
	v_rcp_f32_e32 v65, v65
	s_nop 0
	v_pk_mul_f32 v[64:65], v[82:83], v[64:65] op_sel_hi:[0,1]
	v_pk_mul_f32 v[64:65], v[70:71], v[64:65]
	s_nop 0
	v_cvt_pk_bf16_f32 v75, v64, v65
	v_mad_u64_u32 v[64:65], s[6:7], v138, s14, 0
	v_mov_b32_e32 v66, v65
	v_mad_u64_u32 v[66:67], s[6:7], v139, s14, v[66:67]
	v_mov_b32_e32 v65, v66
	v_lshl_add_u64 v[64:65], v[64:65], 1, v[132:133]
	global_store_dwordx4 v[64:65], v[72:75], off
	v_fmamk_f32 v64, v149, 0x3a800000, v194
	v_rsq_f32_e32 v65, v64
	s_nop 0
	v_mul_f32_e32 v64, 0xbfb8aa3b, v65
	v_pk_mul_f32 v[68:69], v[56:57], v[64:65] op_sel_hi:[1,0]
	v_pk_mul_f32 v[58:59], v[58:59], v[64:65] op_sel_hi:[1,0]
	v_exp_f32_e32 v68, v68
	v_exp_f32_e32 v69, v69
	v_exp_f32_e32 v58, v58
	v_exp_f32_e32 v59, v59
	v_mul_f32_e32 v66, v65, v65
	v_pk_add_f32 v[68:69], v[68:69], 1.0 op_sel_hi:[1,0]
	v_pk_mul_f32 v[56:57], v[60:61], v[56:57]
	v_pk_add_f32 v[58:59], v[58:59], 1.0 op_sel_hi:[1,0]
	v_rcp_f32_e32 v68, v68
	v_rcp_f32_e32 v69, v69
	v_rcp_f32_e32 v58, v58
	v_rcp_f32_e32 v59, v59
	v_pk_mul_f32 v[60:61], v[66:67], v[68:69] op_sel_hi:[0,1]
	v_pk_mul_f32 v[56:57], v[56:57], v[60:61]
	v_pk_mul_f32 v[58:59], v[66:67], v[58:59] op_sel_hi:[0,1]
	v_pk_mul_f32 v[58:59], v[62:63], v[58:59]
	v_cvt_pk_bf16_f32 v56, v56, v57
	s_nop 0
	v_cvt_pk_bf16_f32 v57, v58, v59
	v_pk_mul_f32 v[58:59], v[48:49], v[64:65] op_sel_hi:[1,0]
	v_pk_mul_f32 v[48:49], v[52:53], v[48:49]
	v_exp_f32_e32 v58, v58
	v_exp_f32_e32 v59, v59
	s_nop 0
	v_pk_add_f32 v[58:59], v[58:59], 1.0 op_sel_hi:[1,0]
	s_nop 0
	v_rcp_f32_e32 v58, v58
	v_rcp_f32_e32 v59, v59
	s_nop 0
	v_pk_mul_f32 v[52:53], v[66:67], v[58:59] op_sel_hi:[0,1]
	v_pk_mul_f32 v[48:49], v[48:49], v[52:53]
	s_nop 0
	v_cvt_pk_bf16_f32 v58, v48, v49
	v_pk_mul_f32 v[48:49], v[50:51], v[64:65] op_sel_hi:[1,0]
	s_nop 0
	v_exp_f32_e32 v48, v48
	v_exp_f32_e32 v49, v49
	s_nop 0
	v_pk_add_f32 v[48:49], v[48:49], 1.0 op_sel_hi:[1,0]
	s_nop 0
	v_rcp_f32_e32 v48, v48
	v_rcp_f32_e32 v49, v49
	s_nop 0
	v_pk_mul_f32 v[48:49], v[66:67], v[48:49] op_sel_hi:[0,1]
	v_pk_mul_f32 v[48:49], v[54:55], v[48:49]
	s_nop 0
	v_cvt_pk_bf16_f32 v59, v48, v49
	v_mad_u64_u32 v[48:49], s[6:7], v136, s14, 0
	v_mov_b32_e32 v50, v49
	v_mad_u64_u32 v[50:51], s[6:7], v137, s14, v[50:51]
	v_mov_b32_e32 v49, v50
	v_lshl_add_u64 v[48:49], v[48:49], 1, v[132:133]
	global_store_dwordx4 v[48:49], v[56:59], off
	v_fmamk_f32 v48, v148, 0x3a800000, v194
	v_rsq_f32_e32 v49, v48
	s_nop 0
	v_mul_f32_e32 v48, 0xbfb8aa3b, v49
	v_pk_mul_f32 v[52:53], v[40:41], v[48:49] op_sel_hi:[1,0]
	v_pk_mul_f32 v[42:43], v[42:43], v[48:49] op_sel_hi:[1,0]
	v_exp_f32_e32 v52, v52
	v_exp_f32_e32 v53, v53
	v_exp_f32_e32 v42, v42
	v_exp_f32_e32 v43, v43
	v_mul_f32_e32 v50, v49, v49
	v_pk_add_f32 v[52:53], v[52:53], 1.0 op_sel_hi:[1,0]
	v_pk_mul_f32 v[40:41], v[44:45], v[40:41]
	v_pk_add_f32 v[42:43], v[42:43], 1.0 op_sel_hi:[1,0]
	v_rcp_f32_e32 v52, v52
	v_rcp_f32_e32 v53, v53
	v_rcp_f32_e32 v42, v42
	v_rcp_f32_e32 v43, v43
	v_pk_mul_f32 v[44:45], v[50:51], v[52:53] op_sel_hi:[0,1]
	v_pk_mul_f32 v[40:41], v[40:41], v[44:45]
	v_pk_mul_f32 v[42:43], v[50:51], v[42:43] op_sel_hi:[0,1]
	v_pk_mul_f32 v[42:43], v[46:47], v[42:43]
	v_cvt_pk_bf16_f32 v40, v40, v41
	s_nop 0
	v_cvt_pk_bf16_f32 v41, v42, v43
	v_pk_mul_f32 v[42:43], v[32:33], v[48:49] op_sel_hi:[1,0]
	v_pk_mul_f32 v[32:33], v[36:37], v[32:33]
	v_exp_f32_e32 v42, v42
	v_exp_f32_e32 v43, v43
	s_nop 0
	v_pk_add_f32 v[42:43], v[42:43], 1.0 op_sel_hi:[1,0]
	s_nop 0
	v_rcp_f32_e32 v42, v42
	v_rcp_f32_e32 v43, v43
	s_nop 0
	v_pk_mul_f32 v[36:37], v[50:51], v[42:43] op_sel_hi:[0,1]
	v_pk_mul_f32 v[32:33], v[32:33], v[36:37]
	s_nop 0
	v_cvt_pk_bf16_f32 v42, v32, v33
	v_pk_mul_f32 v[32:33], v[34:35], v[48:49] op_sel_hi:[1,0]
	s_nop 0
	v_exp_f32_e32 v32, v32
	v_exp_f32_e32 v33, v33
	s_nop 0
	v_pk_add_f32 v[32:33], v[32:33], 1.0 op_sel_hi:[1,0]
	s_nop 0
	v_rcp_f32_e32 v32, v32
	v_rcp_f32_e32 v33, v33
	s_nop 0
	v_pk_mul_f32 v[32:33], v[50:51], v[32:33] op_sel_hi:[0,1]
	v_pk_mul_f32 v[32:33], v[38:39], v[32:33]
	s_nop 0
	v_cvt_pk_bf16_f32 v43, v32, v33
	v_mad_u64_u32 v[32:33], s[6:7], v134, s14, 0
	v_mov_b32_e32 v34, v33
	v_mad_u64_u32 v[34:35], s[6:7], v135, s14, v[34:35]
	v_mov_b32_e32 v33, v34
	v_lshl_add_u64 v[32:33], v[32:33], 1, v[132:133]
	global_store_dwordx4 v[32:33], v[40:43], off
	v_fmamk_f32 v32, v146, 0x3a800000, v194
	v_rsq_f32_e32 v33, v32
	s_nop 0
	v_mul_f32_e32 v32, 0xbfb8aa3b, v33
	v_pk_mul_f32 v[36:37], v[24:25], v[32:33] op_sel_hi:[1,0]
	v_pk_mul_f32 v[26:27], v[26:27], v[32:33] op_sel_hi:[1,0]
	v_exp_f32_e32 v36, v36
	v_exp_f32_e32 v37, v37
	v_exp_f32_e32 v26, v26
	v_exp_f32_e32 v27, v27
	v_mul_f32_e32 v34, v33, v33
	v_pk_add_f32 v[36:37], v[36:37], 1.0 op_sel_hi:[1,0]
	v_pk_mul_f32 v[24:25], v[28:29], v[24:25]
	v_pk_add_f32 v[26:27], v[26:27], 1.0 op_sel_hi:[1,0]
	v_rcp_f32_e32 v36, v36
	v_rcp_f32_e32 v37, v37
	v_rcp_f32_e32 v26, v26
	v_rcp_f32_e32 v27, v27
	v_pk_mul_f32 v[28:29], v[34:35], v[36:37] op_sel_hi:[0,1]
	v_pk_mul_f32 v[24:25], v[24:25], v[28:29]
	v_pk_mul_f32 v[26:27], v[34:35], v[26:27] op_sel_hi:[0,1]
	v_pk_mul_f32 v[26:27], v[30:31], v[26:27]
	v_cvt_pk_bf16_f32 v24, v24, v25
	s_nop 0
	v_cvt_pk_bf16_f32 v25, v26, v27
	v_pk_mul_f32 v[26:27], v[16:17], v[32:33] op_sel_hi:[1,0]
	v_pk_mul_f32 v[16:17], v[20:21], v[16:17]
	v_exp_f32_e32 v26, v26
	v_exp_f32_e32 v27, v27
	s_nop 0
	v_pk_add_f32 v[26:27], v[26:27], 1.0 op_sel_hi:[1,0]
	s_nop 0
	v_rcp_f32_e32 v26, v26
	v_rcp_f32_e32 v27, v27
	s_nop 0
	v_pk_mul_f32 v[20:21], v[34:35], v[26:27] op_sel_hi:[0,1]
	v_pk_mul_f32 v[16:17], v[16:17], v[20:21]
	s_nop 0
	v_cvt_pk_bf16_f32 v26, v16, v17
	v_pk_mul_f32 v[16:17], v[18:19], v[32:33] op_sel_hi:[1,0]
	s_nop 0
	v_exp_f32_e32 v16, v16
	v_exp_f32_e32 v17, v17
	s_nop 0
	v_pk_add_f32 v[16:17], v[16:17], 1.0 op_sel_hi:[1,0]
	s_nop 0
	v_rcp_f32_e32 v16, v16
	v_rcp_f32_e32 v17, v17
	s_nop 0
	v_pk_mul_f32 v[16:17], v[34:35], v[16:17] op_sel_hi:[0,1]
	v_pk_mul_f32 v[16:17], v[22:23], v[16:17]
	s_nop 0
	v_cvt_pk_bf16_f32 v27, v16, v17
	v_mad_u64_u32 v[16:17], s[6:7], v130, s14, 0
	v_mov_b32_e32 v18, v17
	v_mad_u64_u32 v[18:19], s[6:7], v131, s14, v[18:19]
	v_mov_b32_e32 v17, v18
	v_lshl_add_u64 v[16:17], v[16:17], 1, v[132:133]
	global_store_dwordx4 v[16:17], v[24:27], off
	v_fmamk_f32 v16, v147, 0x3a800000, v194
	v_rsq_f32_e32 v17, v16
	s_nop 0
	v_mul_f32_e32 v16, 0xbfb8aa3b, v17
	v_pk_mul_f32 v[20:21], v[8:9], v[16:17] op_sel_hi:[1,0]
	v_pk_mul_f32 v[10:11], v[10:11], v[16:17] op_sel_hi:[1,0]
	v_exp_f32_e32 v20, v20
	v_exp_f32_e32 v21, v21
	v_exp_f32_e32 v10, v10
	v_exp_f32_e32 v11, v11
	v_mul_f32_e32 v18, v17, v17
	v_pk_add_f32 v[20:21], v[20:21], 1.0 op_sel_hi:[1,0]
	v_pk_mul_f32 v[8:9], v[12:13], v[8:9]
	v_pk_add_f32 v[10:11], v[10:11], 1.0 op_sel_hi:[1,0]
	v_rcp_f32_e32 v20, v20
	v_rcp_f32_e32 v21, v21
	v_rcp_f32_e32 v10, v10
	v_rcp_f32_e32 v11, v11
	v_pk_mul_f32 v[12:13], v[18:19], v[20:21] op_sel_hi:[0,1]
	v_pk_mul_f32 v[8:9], v[8:9], v[12:13]
	v_pk_mul_f32 v[10:11], v[18:19], v[10:11] op_sel_hi:[0,1]
	v_pk_mul_f32 v[10:11], v[14:15], v[10:11]
	v_cvt_pk_bf16_f32 v8, v8, v9
	s_nop 0
	v_cvt_pk_bf16_f32 v9, v10, v11
	v_pk_mul_f32 v[10:11], v[0:1], v[16:17] op_sel_hi:[1,0]
	v_pk_mul_f32 v[0:1], v[4:5], v[0:1]
	v_exp_f32_e32 v10, v10
	v_exp_f32_e32 v11, v11
	s_nop 0
	v_pk_add_f32 v[10:11], v[10:11], 1.0 op_sel_hi:[1,0]
	s_nop 0
	v_rcp_f32_e32 v10, v10
	v_rcp_f32_e32 v11, v11
	s_nop 0
	v_pk_mul_f32 v[4:5], v[18:19], v[10:11] op_sel_hi:[0,1]
	v_pk_mul_f32 v[0:1], v[0:1], v[4:5]
	s_nop 0
	v_cvt_pk_bf16_f32 v10, v0, v1
	v_pk_mul_f32 v[0:1], v[2:3], v[16:17] op_sel_hi:[1,0]
	s_nop 0
	v_exp_f32_e32 v0, v0
	v_exp_f32_e32 v1, v1
	s_nop 0
	v_pk_add_f32 v[0:1], v[0:1], 1.0 op_sel_hi:[1,0]
	s_nop 0
	v_rcp_f32_e32 v0, v0
	v_rcp_f32_e32 v1, v1
	s_nop 0
	v_pk_mul_f32 v[0:1], v[18:19], v[0:1] op_sel_hi:[0,1]
	v_pk_mul_f32 v[0:1], v[6:7], v[0:1]
	s_nop 0
	v_cvt_pk_bf16_f32 v11, v0, v1
	v_mad_u64_u32 v[0:1], s[6:7], v128, s14, 0
	v_mov_b32_e32 v2, v1
	v_mad_u64_u32 v[2:3], s[6:7], v129, s14, v[2:3]
	v_mov_b32_e32 v1, v2
	v_lshl_add_u64 v[0:1], v[0:1], 1, v[132:133]
	global_store_dwordx4 v[0:1], v[8:11], off
	s_and_b64 vcc, exec, s[4:5]
	s_mov_b64 s[4:5], -1
	s_cbranch_vccnz .LBB0_604

	.amdhsa_kernel _Z10hybrid_fwd4Args
		.amdhsa_group_segment_fixed_size 0
		.amdhsa_private_segment_fixed_size 0
		.amdhsa_kernarg_size 608
		.amdhsa_user_sgpr_count 2
		.amdhsa_user_sgpr_dispatch_ptr 0
		.amdhsa_user_sgpr_queue_ptr 0
		.amdhsa_user_sgpr_kernarg_segment_ptr 1
		.amdhsa_user_sgpr_dispatch_id 0
		.amdhsa_user_sgpr_kernarg_preload_length 0
		.amdhsa_user_sgpr_kernarg_preload_offset 0
		.amdhsa_user_sgpr_private_segment_size 0
		.amdhsa_uses_dynamic_stack 0
		.amdhsa_enable_private_segment 0
		.amdhsa_system_sgpr_workgroup_id_x 1
		.amdhsa_system_sgpr_workgroup_id_y 0
		.amdhsa_system_sgpr_workgroup_id_z 0
		.amdhsa_system_sgpr_workgroup_info 0
		.amdhsa_system_vgpr_workitem_id 0
		.amdhsa_next_free_vgpr 254
		.amdhsa_next_free_sgpr 100
		.amdhsa_accum_offset 256
		.amdhsa_reserve_vcc 1
		.amdhsa_float_round_mode_32 0
		.amdhsa_float_round_mode_16_64 0
		.amdhsa_float_denorm_mode_32 3
		.amdhsa_float_denorm_mode_16_64 3
		.amdhsa_dx10_clamp 1
		.amdhsa_ieee_mode 1
		.amdhsa_fp16_overflow 0
		.amdhsa_tg_split 0
		.amdhsa_exception_fp_ieee_invalid_op 0
		.amdhsa_exception_fp_denorm_src 0
		.amdhsa_exception_fp_ieee_div_zero 0
		.amdhsa_exception_fp_ieee_overflow 0
		.amdhsa_exception_fp_ieee_underflow 0
		.amdhsa_exception_fp_ieee_inexact 0
		.amdhsa_exception_int_div_zero 0
	.end_amdhsa_kernel

amdhsa.kernels:
  - .agpr_count:     0
    .args:
      - .offset:         0
        .size:           352
        .value_kind:     by_value
      - .offset:         352
        .size:           4
        .value_kind:     hidden_block_count_x
      - .offset:         356
        .size:           4
        .value_kind:     hidden_block_count_y
      - .offset:         360
        .size:           4
        .value_kind:     hidden_block_count_z
      - .offset:         364
        .size:           2
        .value_kind:     hidden_group_size_x
      - .offset:         366
        .size:           2
        .value_kind:     hidden_group_size_y
      - .offset:         368
        .size:           2
        .value_kind:     hidden_group_size_z
      - .offset:         370
        .size:           2
        .value_kind:     hidden_remainder_x
      - .offset:         372
        .size:           2
        .value_kind:     hidden_remainder_y
      - .offset:         374
        .size:           2
        .value_kind:     hidden_remainder_z
      - .offset:         392
        .size:           8
        .value_kind:     hidden_global_offset_x
      - .offset:         400
        .size:           8
        .value_kind:     hidden_global_offset_y
      - .offset:         408
        .size:           8
        .value_kind:     hidden_global_offset_z
      - .offset:         416
        .size:           2
        .value_kind:     hidden_grid_dims
      - .offset:         472
        .size:           4
        .value_kind:     hidden_dynamic_lds_size
    .group_segment_fixed_size: 0
    .kernarg_segment_align: 8
    .kernarg_segment_size: 608
    .language:       OpenCL C
    .language_version:
      - 2
      - 0
    .max_flat_workgroup_size: 512
    .name:           _Z10hybrid_fwd4Args
    .private_segment_fixed_size: 0
    .sgpr_count:     106
    .sgpr_spill_count: 171
    .symbol:         _Z10hybrid_fwd4Args.kd
    .uniform_work_group_size: 1
    .uses_dynamic_stack: false
    .vgpr_count:     254
    .vgpr_spill_count: 0
    .wavefront_size: 64
